# v51 + phase 0: the 64 small weight transposes spread over block groups (were serialized on 8 blocks) and big weight transposes remapped for full-line writes
# speedup vs baseline: 1.0114x; 1.0114x over previous
.LBB0_44:
	v_lshrrev_b32_e32 v3, 13, v2
	v_bfe_u32 v5, v2, 3, 3
	v_lshl_or_b32 v3, v3, 3, v5
	v_bfe_u32 v6, v2, 6, 7
	v_and_b32_e32 v5, 7, v2
	v_lshl_or_b32 v6, v6, 3, v5
	v_lshlrev_b32_e32 v4, 3, v3
	s_waitcnt vmcnt(0)
	v_or_b32_e32 v10, 2, v4
	v_or_b32_e32 v12, 3, v4
	v_or_b32_e32 v14, 4, v4
	v_or_b32_e32 v16, 5, v4
	v_or_b32_e32 v18, 6, v4
	v_or_b32_e32 v20, 7, v4
	v_or_b32_e32 v8, 1, v4
	v_ashrrev_i32_e32 v7, 31, v6
	v_ashrrev_i32_e32 v11, 31, v10
	v_ashrrev_i32_e32 v13, 31, v12
	v_ashrrev_i32_e32 v15, 31, v14
	v_ashrrev_i32_e32 v17, 31, v16
	v_ashrrev_i32_e32 v19, 31, v18
	v_ashrrev_i32_e32 v21, 31, v20
	v_ashrrev_i32_e32 v5, 31, v4
	v_ashrrev_i32_e32 v9, 31, v8
	v_lshl_add_u64 v[24:25], v[6:7], 2, s[36:37]
	v_lshlrev_b64 v[10:11], 12, v[10:11]
	v_lshlrev_b64 v[12:13], 12, v[12:13]
	v_lshlrev_b64 v[14:15], 12, v[14:15]
	v_lshlrev_b64 v[16:17], 12, v[16:17]
	v_lshlrev_b64 v[18:19], 12, v[18:19]
	v_lshlrev_b64 v[20:21], 12, v[20:21]
	v_lshlrev_b64 v[22:23], 12, v[4:5]
	v_lshlrev_b64 v[8:9], 12, v[8:9]
	v_lshl_add_u64 v[10:11], v[24:25], 0, v[10:11]
	v_lshl_add_u64 v[12:13], v[24:25], 0, v[12:13]
	v_lshl_add_u64 v[14:15], v[24:25], 0, v[14:15]
	v_lshl_add_u64 v[16:17], v[24:25], 0, v[16:17]
	v_lshl_add_u64 v[18:19], v[24:25], 0, v[18:19]
	v_lshl_add_u64 v[20:21], v[24:25], 0, v[20:21]
	v_lshl_add_u64 v[22:23], v[24:25], 0, v[22:23]
	v_lshl_add_u64 v[8:9], v[24:25], 0, v[8:9]
	global_load_dword v3, v[20:21], off
	s_nop 0
	global_load_dword v18, v[18:19], off
	s_nop 0
	global_load_dword v16, v[16:17], off
	s_nop 0
	global_load_dword v14, v[14:15], off
	s_nop 0
	global_load_dword v12, v[12:13], off
	s_nop 0
	global_load_dword v10, v[10:11], off
	s_nop 0
	global_load_dword v11, v[8:9], off
	global_load_dword v13, v[22:23], off
	v_lshlrev_b64 v[6:7], 11, v[6:7]
	v_lshl_add_u64 v[6:7], s[10:11], 0, v[6:7]
	v_add_u32_e32 v2, v2, v1
	v_lshl_add_u64 v[8:9], v[4:5], 1, v[6:7]
	v_cmp_lt_i32_e64 s[0:1], s42, v2
	s_or_b64 s[38:39], s[0:1], s[38:39]
	s_waitcnt vmcnt(7)
	v_bfe_u32 v4, v3, 16, 1
	s_waitcnt vmcnt(6)
	v_bfe_u32 v5, v18, 16, 1
	s_waitcnt vmcnt(5)
	v_bfe_u32 v6, v16, 16, 1
	s_waitcnt vmcnt(4)
	v_bfe_u32 v7, v14, 16, 1
	s_waitcnt vmcnt(3)
	v_bfe_u32 v15, v12, 16, 1
	s_waitcnt vmcnt(2)
	v_bfe_u32 v17, v10, 16, 1
	s_waitcnt vmcnt(1)
	v_bfe_u32 v19, v11, 16, 1
	s_waitcnt vmcnt(0)
	v_bfe_u32 v20, v13, 16, 1
	v_add3_u32 v13, v13, v20, s33
	v_add3_u32 v11, v11, v19, s33
	v_add3_u32 v10, v10, v17, s33
	v_add3_u32 v12, v12, v15, s33
	v_add3_u32 v14, v14, v7, s33
	v_add3_u32 v6, v16, v6, s33
	v_add3_u32 v5, v18, v5, s33
	v_add3_u32 v3, v3, v4, s33
	v_perm_b32 v7, v3, v5, s96
	v_perm_b32 v6, v6, v14, s96
	v_perm_b32 v5, v12, v10, s96
	v_perm_b32 v4, v11, v13, s96
	global_store_dwordx4 v[8:9], v[4:7], off
	s_andn2_b64 exec, exec, s[38:39]
	s_cbranch_execnz .LBB0_44
	s_or_b64 exec, exec, s[38:39]
	v_readlane_b32 s48, v253, 43
	v_readlane_b32 s60, v253, 55
	v_readlane_b32 s61, v253, 56
	s_add_u32 s34, s60, s34
	s_addc_u32 s35, s61, s35
	s_add_u32 s36, s10, 0x200000
	s_addc_u32 s37, s11, 0
	s_mov_b64 s[38:39], 0
	v_mov_b32_e32 v2, v0
	v_readlane_b32 s49, v253, 44
	v_readlane_b32 s50, v253, 45
	v_readlane_b32 s51, v253, 46
	v_readlane_b32 s52, v253, 47
	v_readlane_b32 s53, v253, 48
	v_readlane_b32 s54, v253, 49
	v_readlane_b32 s55, v253, 50
	v_readlane_b32 s56, v253, 51
	v_readlane_b32 s57, v253, 52
	v_readlane_b32 s58, v253, 53
	v_readlane_b32 s59, v253, 54
	v_readlane_b32 s62, v253, 57
	v_readlane_b32 s63, v253, 58
.LBB0_46:
	v_lshrrev_b32_e32 v3, 13, v2
	v_bfe_u32 v5, v2, 3, 3
	v_lshl_or_b32 v3, v3, 3, v5
	v_bfe_u32 v6, v2, 6, 7
	v_and_b32_e32 v5, 7, v2
	v_lshl_or_b32 v6, v6, 3, v5
	v_lshlrev_b32_e32 v4, 3, v3
	v_or_b32_e32 v10, 2, v4
	v_or_b32_e32 v12, 3, v4
	v_or_b32_e32 v14, 4, v4
	v_or_b32_e32 v16, 5, v4
	v_or_b32_e32 v18, 6, v4
	v_or_b32_e32 v20, 7, v4
	v_or_b32_e32 v8, 1, v4
	v_ashrrev_i32_e32 v7, 31, v6
	v_ashrrev_i32_e32 v11, 31, v10
	v_ashrrev_i32_e32 v13, 31, v12
	v_ashrrev_i32_e32 v15, 31, v14
	v_ashrrev_i32_e32 v17, 31, v16
	v_ashrrev_i32_e32 v19, 31, v18
	v_ashrrev_i32_e32 v21, 31, v20
	v_ashrrev_i32_e32 v5, 31, v4
	v_ashrrev_i32_e32 v9, 31, v8
	v_lshl_add_u64 v[24:25], v[6:7], 2, s[34:35]
	v_lshlrev_b64 v[10:11], 12, v[10:11]
	v_lshlrev_b64 v[12:13], 12, v[12:13]
	v_lshlrev_b64 v[14:15], 12, v[14:15]
	v_lshlrev_b64 v[16:17], 12, v[16:17]
	v_lshlrev_b64 v[18:19], 12, v[18:19]
	v_lshlrev_b64 v[20:21], 12, v[20:21]
	v_lshlrev_b64 v[22:23], 12, v[4:5]
	v_lshlrev_b64 v[8:9], 12, v[8:9]
	v_lshl_add_u64 v[10:11], v[24:25], 0, v[10:11]
	v_lshl_add_u64 v[12:13], v[24:25], 0, v[12:13]
	v_lshl_add_u64 v[14:15], v[24:25], 0, v[14:15]
	v_lshl_add_u64 v[16:17], v[24:25], 0, v[16:17]
	v_lshl_add_u64 v[18:19], v[24:25], 0, v[18:19]
	v_lshl_add_u64 v[20:21], v[24:25], 0, v[20:21]
	v_lshl_add_u64 v[22:23], v[24:25], 0, v[22:23]
	v_lshl_add_u64 v[8:9], v[24:25], 0, v[8:9]
	global_load_dword v3, v[20:21], off
	s_nop 0
	global_load_dword v18, v[18:19], off
	s_nop 0
	global_load_dword v16, v[16:17], off
	s_nop 0
	global_load_dword v14, v[14:15], off
	s_nop 0
	global_load_dword v12, v[12:13], off
	s_nop 0
	global_load_dword v10, v[10:11], off
	s_nop 0
	global_load_dword v11, v[8:9], off
	global_load_dword v13, v[22:23], off
	v_lshlrev_b64 v[6:7], 11, v[6:7]
	v_lshl_add_u64 v[6:7], s[36:37], 0, v[6:7]
	v_add_u32_e32 v2, v2, v1
	v_lshl_add_u64 v[8:9], v[4:5], 1, v[6:7]
	v_cmp_lt_i32_e64 s[0:1], s42, v2
	s_or_b64 s[38:39], s[0:1], s[38:39]
	s_waitcnt vmcnt(7)
	v_bfe_u32 v4, v3, 16, 1
	s_waitcnt vmcnt(6)
	v_bfe_u32 v5, v18, 16, 1
	s_waitcnt vmcnt(5)
	v_bfe_u32 v6, v16, 16, 1
	s_waitcnt vmcnt(4)
	v_bfe_u32 v7, v14, 16, 1
	s_waitcnt vmcnt(3)
	v_bfe_u32 v15, v12, 16, 1
	s_waitcnt vmcnt(2)
	v_bfe_u32 v17, v10, 16, 1
	s_waitcnt vmcnt(1)
	v_bfe_u32 v19, v11, 16, 1
	s_waitcnt vmcnt(0)
	v_bfe_u32 v20, v13, 16, 1
	v_add3_u32 v13, v13, v20, s33
	v_add3_u32 v11, v11, v19, s33
	v_add3_u32 v10, v10, v17, s33
	v_add3_u32 v12, v12, v15, s33
	v_add3_u32 v14, v14, v7, s33
	v_add3_u32 v6, v16, v6, s33
	v_add3_u32 v5, v18, v5, s33
	v_add3_u32 v3, v3, v4, s33
	v_perm_b32 v7, v3, v5, s96
	v_perm_b32 v6, v6, v14, s96
	v_perm_b32 v5, v12, v10, s96
	v_perm_b32 v4, v11, v13, s96
	global_store_dwordx4 v[8:9], v[4:7], off
	s_andn2_b64 exec, exec, s[38:39]
	s_cbranch_execnz .LBB0_46
	s_or_b64 exec, exec, s[38:39]

.LBB0_50:
	v_lshrrev_b32_e32 v3, 13, v2
	v_bfe_u32 v5, v2, 3, 3
	v_lshl_or_b32 v3, v3, 3, v5
	v_bfe_u32 v6, v2, 6, 7
	v_and_b32_e32 v5, 7, v2
	v_lshl_or_b32 v6, v6, 3, v5
	v_lshlrev_b32_e32 v4, 3, v3
	s_waitcnt vmcnt(0)
	v_or_b32_e32 v10, 2, v4
	v_or_b32_e32 v12, 3, v4
	v_or_b32_e32 v14, 4, v4
	v_or_b32_e32 v16, 5, v4
	v_or_b32_e32 v18, 6, v4
	v_or_b32_e32 v20, 7, v4
	v_or_b32_e32 v8, 1, v4
	v_ashrrev_i32_e32 v7, 31, v6
	v_ashrrev_i32_e32 v11, 31, v10
	v_ashrrev_i32_e32 v13, 31, v12
	v_ashrrev_i32_e32 v15, 31, v14
	v_ashrrev_i32_e32 v17, 31, v16
	v_ashrrev_i32_e32 v19, 31, v18
	v_ashrrev_i32_e32 v21, 31, v20
	v_ashrrev_i32_e32 v5, 31, v4
	v_ashrrev_i32_e32 v9, 31, v8
	v_lshl_add_u64 v[24:25], v[6:7], 2, s[34:35]
	v_lshlrev_b64 v[10:11], 12, v[10:11]
	v_lshlrev_b64 v[12:13], 12, v[12:13]
	v_lshlrev_b64 v[14:15], 12, v[14:15]
	v_lshlrev_b64 v[16:17], 12, v[16:17]
	v_lshlrev_b64 v[18:19], 12, v[18:19]
	v_lshlrev_b64 v[20:21], 12, v[20:21]
	v_lshlrev_b64 v[22:23], 12, v[4:5]
	v_lshlrev_b64 v[8:9], 12, v[8:9]
	v_lshl_add_u64 v[10:11], v[24:25], 0, v[10:11]
	v_lshl_add_u64 v[12:13], v[24:25], 0, v[12:13]
	v_lshl_add_u64 v[14:15], v[24:25], 0, v[14:15]
	v_lshl_add_u64 v[16:17], v[24:25], 0, v[16:17]
	v_lshl_add_u64 v[18:19], v[24:25], 0, v[18:19]
	v_lshl_add_u64 v[20:21], v[24:25], 0, v[20:21]
	v_lshl_add_u64 v[22:23], v[24:25], 0, v[22:23]
	v_lshl_add_u64 v[8:9], v[24:25], 0, v[8:9]
	global_load_dword v3, v[20:21], off
	s_nop 0
	global_load_dword v18, v[18:19], off
	s_nop 0
	global_load_dword v16, v[16:17], off
	s_nop 0
	global_load_dword v14, v[14:15], off
	s_nop 0
	global_load_dword v12, v[12:13], off
	s_nop 0
	global_load_dword v10, v[10:11], off
	s_nop 0
	global_load_dword v11, v[8:9], off
	global_load_dword v13, v[22:23], off
	v_lshlrev_b64 v[6:7], 11, v[6:7]
	v_lshl_add_u64 v[6:7], s[36:37], 0, v[6:7]
	v_add_u32_e32 v2, v2, v1
	v_lshl_add_u64 v[8:9], v[4:5], 1, v[6:7]
	v_cmp_lt_i32_e64 s[0:1], s42, v2
	s_or_b64 s[38:39], s[0:1], s[38:39]
	s_waitcnt vmcnt(7)
	v_bfe_u32 v4, v3, 16, 1
	s_waitcnt vmcnt(6)
	v_bfe_u32 v5, v18, 16, 1
	s_waitcnt vmcnt(5)
	v_bfe_u32 v6, v16, 16, 1
	s_waitcnt vmcnt(4)
	v_bfe_u32 v7, v14, 16, 1
	s_waitcnt vmcnt(3)
	v_bfe_u32 v15, v12, 16, 1
	s_waitcnt vmcnt(2)
	v_bfe_u32 v17, v10, 16, 1
	s_waitcnt vmcnt(1)
	v_bfe_u32 v19, v11, 16, 1
	s_waitcnt vmcnt(0)
	v_bfe_u32 v20, v13, 16, 1
	v_add3_u32 v13, v13, v20, s33
	v_add3_u32 v11, v11, v19, s33
	v_add3_u32 v10, v10, v17, s33
	v_add3_u32 v12, v12, v15, s33
	v_add3_u32 v14, v14, v7, s33
	v_add3_u32 v6, v16, v6, s33
	v_add3_u32 v5, v18, v5, s33
	v_add3_u32 v3, v3, v4, s33
	v_perm_b32 v7, v3, v5, s96
	v_perm_b32 v6, v6, v14, s96
	v_perm_b32 v5, v12, v10, s96
	v_perm_b32 v4, v11, v13, s96
	global_store_dwordx4 v[8:9], v[4:7], off
	s_andn2_b64 exec, exec, s[38:39]
	s_cbranch_execnz .LBB0_50
	s_or_b64 exec, exec, s[38:39]
	s_add_u32 s12, s88, s12
	s_addc_u32 s13, s89, s13
	s_add_u32 s10, s10, 0x600000
	s_addc_u32 s11, s11, 0
	s_mov_b64 s[34:35], 0
	v_mov_b32_e32 v2, v0
.LBB0_52:
	v_lshrrev_b32_e32 v3, 13, v2
	v_bfe_u32 v5, v2, 3, 3
	v_lshl_or_b32 v3, v3, 3, v5
	v_bfe_u32 v6, v2, 6, 7
	v_and_b32_e32 v5, 7, v2
	v_lshl_or_b32 v6, v6, 3, v5
	v_lshlrev_b32_e32 v4, 3, v3
	v_or_b32_e32 v10, 2, v4
	v_or_b32_e32 v12, 3, v4
	v_or_b32_e32 v14, 4, v4
	v_or_b32_e32 v16, 5, v4
	v_or_b32_e32 v18, 6, v4
	v_or_b32_e32 v20, 7, v4
	v_or_b32_e32 v8, 1, v4
	v_ashrrev_i32_e32 v7, 31, v6
	v_ashrrev_i32_e32 v11, 31, v10
	v_ashrrev_i32_e32 v13, 31, v12
	v_ashrrev_i32_e32 v15, 31, v14
	v_ashrrev_i32_e32 v17, 31, v16
	v_ashrrev_i32_e32 v19, 31, v18
	v_ashrrev_i32_e32 v21, 31, v20
	v_ashrrev_i32_e32 v5, 31, v4
	v_ashrrev_i32_e32 v9, 31, v8
	v_lshl_add_u64 v[24:25], v[6:7], 2, s[12:13]
	v_lshlrev_b64 v[10:11], 12, v[10:11]
	v_lshlrev_b64 v[12:13], 12, v[12:13]
	v_lshlrev_b64 v[14:15], 12, v[14:15]
	v_lshlrev_b64 v[16:17], 12, v[16:17]
	v_lshlrev_b64 v[18:19], 12, v[18:19]
	v_lshlrev_b64 v[20:21], 12, v[20:21]
	v_lshlrev_b64 v[22:23], 12, v[4:5]
	v_lshlrev_b64 v[8:9], 12, v[8:9]
	v_lshl_add_u64 v[10:11], v[24:25], 0, v[10:11]
	v_lshl_add_u64 v[12:13], v[24:25], 0, v[12:13]
	v_lshl_add_u64 v[14:15], v[24:25], 0, v[14:15]
	v_lshl_add_u64 v[16:17], v[24:25], 0, v[16:17]
	v_lshl_add_u64 v[18:19], v[24:25], 0, v[18:19]
	v_lshl_add_u64 v[20:21], v[24:25], 0, v[20:21]
	v_lshl_add_u64 v[22:23], v[24:25], 0, v[22:23]
	v_lshl_add_u64 v[8:9], v[24:25], 0, v[8:9]
	global_load_dword v3, v[20:21], off
	s_nop 0
	global_load_dword v18, v[18:19], off
	s_nop 0
	global_load_dword v16, v[16:17], off
	s_nop 0
	global_load_dword v14, v[14:15], off
	s_nop 0
	global_load_dword v12, v[12:13], off
	s_nop 0
	global_load_dword v10, v[10:11], off
	s_nop 0
	global_load_dword v11, v[8:9], off
	global_load_dword v13, v[22:23], off
	v_lshlrev_b64 v[6:7], 11, v[6:7]
	v_lshl_add_u64 v[6:7], s[10:11], 0, v[6:7]
	v_add_u32_e32 v2, v2, v1
	v_lshl_add_u64 v[8:9], v[4:5], 1, v[6:7]
	v_cmp_lt_i32_e64 s[0:1], s42, v2
	s_or_b64 s[34:35], s[0:1], s[34:35]
	s_waitcnt vmcnt(7)
	v_bfe_u32 v4, v3, 16, 1
	s_waitcnt vmcnt(6)
	v_bfe_u32 v5, v18, 16, 1
	s_waitcnt vmcnt(5)
	v_bfe_u32 v6, v16, 16, 1
	s_waitcnt vmcnt(4)
	v_bfe_u32 v7, v14, 16, 1
	s_waitcnt vmcnt(3)
	v_bfe_u32 v15, v12, 16, 1
	s_waitcnt vmcnt(2)
	v_bfe_u32 v17, v10, 16, 1
	s_waitcnt vmcnt(1)
	v_bfe_u32 v19, v11, 16, 1
	s_waitcnt vmcnt(0)
	v_bfe_u32 v20, v13, 16, 1
	v_add3_u32 v13, v13, v20, s33
	v_add3_u32 v11, v11, v19, s33
	v_add3_u32 v10, v10, v17, s33
	v_add3_u32 v12, v12, v15, s33
	v_add3_u32 v14, v14, v7, s33
	v_add3_u32 v6, v16, v6, s33
	v_add3_u32 v5, v18, v5, s33
	v_add3_u32 v3, v3, v4, s33
	v_perm_b32 v7, v3, v5, s96
	v_perm_b32 v6, v6, v14, s96
	v_perm_b32 v5, v12, v10, s96
	v_perm_b32 v4, v11, v13, s96
	global_store_dwordx4 v[8:9], v[4:7], off
	s_andn2_b64 exec, exec, s[34:35]
	s_cbranch_execnz .LBB0_52
	s_or_b64 exec, exec, s[34:35]

.LBB0_56:
	s_lshl_b32 s0, s8, 3
	s_add_i32 s0, s0, s11
	s_lshl_b32 s0, s0, 11
	v_subrev_u32_e32 v240, s0, v0
	s_movk_i32 s2, 0x800
	v_cmp_gt_u32_e64 s[0:1], s2, v240
	s_nop 1
	s_and_saveexec_b64 s[12:13], s[0:1]
	s_cbranch_execz .LBB0_55
	s_lshl_b32 s0, s11, 14
	s_add_i32 s2, s0, s10
	s_lshl_b64 s[14:15], s[2:3], 2
	s_add_u32 s34, s84, s14
	s_addc_u32 s35, s85, s15
	s_add_i32 s2, s2, s10
	s_lshl_b64 s[0:1], s[2:3], 1
	s_add_u32 s36, s44, s0
	s_addc_u32 s37, s45, s1
	s_mov_b64 s[38:39], 0
	v_mov_b32_e32 v2, v240
.LBB0_58:
	v_ashrrev_i32_e32 v3, 31, v2
	v_lshrrev_b32_e32 v3, 25, v3
	v_add_u32_e32 v3, v2, v3
	v_ashrrev_i32_e32 v5, 7, v3
	v_and_b32_e32 v3, 0xffffff80, v3
	s_waitcnt vmcnt(0)
	v_lshlrev_b32_e32 v6, 3, v5
	v_sub_u32_e32 v4, v2, v3
	v_or_b32_e32 v10, 2, v6
	v_or_b32_e32 v12, 3, v6
	v_or_b32_e32 v14, 4, v6
	v_or_b32_e32 v16, 5, v6
	v_or_b32_e32 v18, 6, v6
	v_or_b32_e32 v20, 7, v6
	v_ashrrev_i32_e32 v5, 31, v4
	v_ashrrev_i32_e32 v7, 31, v6
	v_or_b32_e32 v8, 1, v6
	v_ashrrev_i32_e32 v11, 31, v10
	v_ashrrev_i32_e32 v13, 31, v12
	v_ashrrev_i32_e32 v15, 31, v14
	v_ashrrev_i32_e32 v17, 31, v16
	v_ashrrev_i32_e32 v19, 31, v18
	v_ashrrev_i32_e32 v21, 31, v20
	v_lshl_add_u64 v[22:23], v[4:5], 2, s[34:35]
	v_lshlrev_b64 v[24:25], 9, v[6:7]
	v_ashrrev_i32_e32 v9, 31, v8
	v_lshlrev_b64 v[10:11], 9, v[10:11]
	v_lshlrev_b64 v[12:13], 9, v[12:13]
	v_lshlrev_b64 v[14:15], 9, v[14:15]
	v_lshlrev_b64 v[16:17], 9, v[16:17]
	v_lshlrev_b64 v[18:19], 9, v[18:19]
	v_lshlrev_b64 v[20:21], 9, v[20:21]
	v_lshl_add_u64 v[24:25], v[22:23], 0, v[24:25]
	v_lshlrev_b64 v[8:9], 9, v[8:9]
	v_lshl_add_u64 v[10:11], v[22:23], 0, v[10:11]
	v_lshl_add_u64 v[12:13], v[22:23], 0, v[12:13]
	v_lshl_add_u64 v[14:15], v[22:23], 0, v[14:15]
	v_lshl_add_u64 v[16:17], v[22:23], 0, v[16:17]
	v_lshl_add_u64 v[18:19], v[22:23], 0, v[18:19]
	v_lshl_add_u64 v[20:21], v[22:23], 0, v[20:21]
	v_lshl_add_u64 v[8:9], v[22:23], 0, v[8:9]
	global_load_dword v3, v[24:25], off
	s_nop 0
	global_load_dword v20, v[20:21], off
	s_nop 0
	global_load_dword v18, v[18:19], off
	s_nop 0
	global_load_dword v16, v[16:17], off
	s_nop 0
	global_load_dword v14, v[14:15], off
	s_nop 0
	global_load_dword v12, v[12:13], off
	s_nop 0
	global_load_dword v10, v[10:11], off
	s_nop 0
	global_load_dword v11, v[8:9], off
	v_lshlrev_b64 v[4:5], 8, v[4:5]
	v_lshl_add_u64 v[4:5], s[36:37], 0, v[4:5]
	v_add_u32_e32 v2, v2, v1
	v_lshl_add_u64 v[8:9], v[6:7], 1, v[4:5]
	v_cmp_lt_i32_e64 s[0:1], s43, v2
	s_or_b64 s[38:39], s[0:1], s[38:39]
	s_waitcnt vmcnt(7)
	v_bfe_u32 v4, v3, 16, 1
	s_waitcnt vmcnt(6)
	v_bfe_u32 v5, v20, 16, 1
	s_waitcnt vmcnt(5)
	v_bfe_u32 v6, v18, 16, 1
	s_waitcnt vmcnt(4)
	v_bfe_u32 v7, v16, 16, 1
	s_waitcnt vmcnt(3)
	v_bfe_u32 v13, v14, 16, 1
	s_waitcnt vmcnt(2)
	v_bfe_u32 v15, v12, 16, 1
	s_waitcnt vmcnt(1)
	v_bfe_u32 v17, v10, 16, 1
	s_waitcnt vmcnt(0)
	v_bfe_u32 v19, v11, 16, 1
	v_add3_u32 v3, v3, v4, s33
	v_add3_u32 v4, v11, v19, s33
	v_add3_u32 v10, v10, v17, s33
	v_add3_u32 v11, v12, v15, s33
	v_add3_u32 v12, v14, v13, s33
	v_add3_u32 v13, v16, v7, s33
	v_add3_u32 v6, v18, v6, s33
	v_add3_u32 v5, v20, v5, s33
	v_perm_b32 v7, v5, v6, s96
	v_perm_b32 v6, v13, v12, s96
	v_perm_b32 v5, v11, v10, s96
	v_perm_b32 v4, v4, v3, s96
	global_store_dwordx4 v[8:9], v[4:7], off
	s_andn2_b64 exec, exec, s[38:39]
	s_cbranch_execnz .LBB0_58
	s_or_b64 exec, exec, s[38:39]
	s_add_u32 s14, s16, s14
	s_addc_u32 s15, s17, s15
	s_add_u32 s34, s36, 0x40000
	s_addc_u32 s35, s37, 0
	s_mov_b64 s[36:37], 0
	v_mov_b32_e32 v2, v240
